# v25
# baseline (speedup 1.0000x reference)
; DEVI void attn_unit(const Params& p, char* lds, int au) {
;     ...
;     if (i == 1) {
;       float mm = fminf(mrun[0], mrun[1]);
; #pragma unroll
;       for (int ofs = 1; ofs < 16; ofs <<= 1) mm = fminf(mm, __shfl_xor(mm, ofs));
;       float* hx = (float*)(lds + 86016);
;       if (lane == 0) hx[wid] = qkb - mm;
;       __syncthreads();
;       const float X = fmaxf(fmaxf(fmaxf(hx[0], hx[1]), fmaxf(hx[2], hx[3])), fmaxf(fmaxf(hx[4], hx[5]), fmaxf(hx[6], hx[7]))) + 152.f;
;       float tf = X / (64.f * slope2) + 1.f;
;       const int tmax = tf > 1000.f ? 1000 : (int)tf;
;       nL = leftAvail < tmax ? leftAvail : tmax;
;       const int nR = rightAvail < tmax ? rightAvail : tmax;
;       total = 2 + nL + nR;
;     }
.LBB0_204:
	s_or_b64 exec, exec, s[14:15]
	v_pk_add_f32 v[138:139], v[146:147], v[138:139]
	v_pk_add_f32 v[120:121], v[152:153], v[120:121]
	v_pk_add_f32 v[114:115], v[114:115], v[138:139]
	v_pk_add_f32 v[106:107], v[106:107], v[120:121]
	v_pk_add_f32 v[114:115], v[154:155], v[114:115]
	v_mov_b32_e32 v63, 0x15010
	v_pk_add_f32 v[138:139], v[148:149], v[114:115]
	v_pk_add_f32 v[114:115], v[116:117], v[118:119]
	s_waitcnt vmcnt(0) lgkmcnt(0)
	v_pk_add_f32 v[118:119], v[108:109], v[114:115]
	s_barrier
	ds_read_b128 v[114:117], v174
	v_pk_add_f32 v[96:97], v[96:97], v[106:107]
	ds_read_b128 v[106:109], v63
	v_mul_f32_e32 v0, 0x42800000, v133
	v_pk_add_f32 v[94:95], v[94:95], v[118:119]
	s_waitcnt lgkmcnt(1)
	v_max_f32_e32 v63, v115, v115
	v_max_f32_e32 v65, v114, v114
	s_waitcnt lgkmcnt(0)
	v_max_f32_e32 v109, v109, v109
	v_max_f32_e32 v108, v108, v108
	v_max_f32_e32 v63, v65, v63
	v_max_f32_e32 v65, v117, v117
	v_max_f32_e32 v114, v116, v116
	v_max_f32_e32 v108, v108, v109
	v_max_f32_e32 v65, v114, v65
	v_max3_f32 v106, v106, v107, v108
	v_max3_f32 v63, v63, v65, v106
	v_add_f32_e32 v63, 0x43180000, v63
	v_div_scale_f32 v65, s[6:7], v0, v0, v63
	v_rcp_f32_e32 v106, v65
	v_pk_add_f32 v[136:137], v[140:141], v[136:137]
	v_pk_add_f32 v[140:141], v[86:87], v[94:95]
	v_pk_add_f32 v[136:137], v[142:143], v[136:137]
	v_fma_f32 v86, -v65, v106, 1.0
	v_fmac_f32_e32 v106, v86, v106
	v_div_scale_f32 v86, vcc, v63, v0, v63
	v_mul_f32_e32 v87, v86, v106
	v_pk_add_f32 v[142:143], v[88:89], v[96:97]
	v_fma_f32 v88, -v65, v87, v86
	v_fmac_f32_e32 v87, v88, v106
	v_fma_f32 v65, -v65, v87, v86
	v_div_fmas_f32 v65, v65, v106, v87
	v_div_fixup_f32 v0, v65, v0, v63
	v_add_f32_e32 v0, 1.0, v0
	s_mov_b32 s6, 0x447a0000
	v_cmp_nle_f32_e32 vcc, s6, v0
	v_mov_b32_e32 v63, 0x447a0000
	s_and_b64 s[2:3], s[2:3], exec
	v_cndmask_b32_e32 v0, v63, v0, vcc
	v_cvt_i32_f32_e32 v0, v0
	s_cselect_b32 s2, 0x100, 32
	s_sub_i32 s2, s2, s19
	v_pk_add_f32 v[136:137], v[144:145], v[136:137]
	v_readfirstlane_b32 s3, v0
	s_min_i32 s6, s76, s3
	s_min_i32 s2, s2, s3
	s_add_i32 s2, s6, s2
	s_add_i32 s7, s2, 2
	v_pk_add_f32 v[136:137], v[150:151], v[136:137]
	s_mov_b32 s11, 2
	s_cmp_lt_i32 s7, 3
	s_barrier
	s_cbranch_scc1 .LBB0_223
	v_readfirstlane_b32 s34, v179
	s_and_b64 vcc, exec, s[4:5]
	s_cbranch_vccnz .Lprio_skip
	s_setprio 1

; DEVI void attn_unit(const Params& p, char* lds, int au) {
;     ...
;     if (i + 1 < total) {
;       const int i2 = i + 1;
;       const int ktn = (i2 < 2) ? ktd + i2 : ((i2 - 1) <= nL ? ktd - (i2 - 1) : ktd + 1 + (i2 - 1 - nL));
;       ISSUEKV(ktn, cur ^ 1, vnext);
;     }
.LBB0_222:
	s_add_i32 s3, s2, 3
	s_cmp_gt_i32 s18, s6
	s_cselect_b32 s22, s3, s8
	s_lshl_b32 s19, s20, 14
	s_xor_b32 s20, s19, 0x4000
	s_ashr_i32 s23, s22, 31
	s_mul_i32 s36, s22, 0x91000
	s_mov_b32 s37, 0
	s_lshl_b64 s[38:39], s[22:23], 17
	s_add_i32 s20, s20, s34
	s_lshl_b32 s3, s11, 14
	s_add_i32 s3, s3, s34
	s_add_i32 s3, s3, 0x8000
	v_lshl_add_u64 v[96:97], v[128:129], 0, s[36:37]
	v_lshl_add_u64 v[94:95], v[130:131], 0, s[38:39]
	s_mov_b32 m0, s20
	s_add_i32 s36, s36, 0x48800
	global_load_lds_dwordx4 v[96:97], off
	s_mov_b32 m0, s3
	v_lshl_add_u64 v[96:97], v[128:129], 0, s[36:37]
	s_add_i32 s20, s20, 0x2000
	global_load_lds_dwordx4 v[94:95], off
	s_mov_b32 m0, s20
	v_lshl_add_u64 v[94:95], v[94:95], 0, s[28:29]
	s_add_i32 s3, s3, 0x2000
	global_load_lds_dwordx4 v[96:97], off
	s_mov_b32 m0, s3
	s_nop 0
	global_load_lds_dwordx4 v[94:95], off
	s_and_b64 vcc, exec, s[4:5]
	s_cbranch_vccz .LBB0_209
	s_branch .LBB0_210
